# SSD scan loop hand-scheduled: LDS fragment reads two k-slices ahead under counted waits, exact vmcnt, and the per-step decay weights folded into the 4 B^T fragments (f32 product, bf16 MFMA operand) in
# speedup vs baseline: 1.0302x; 1.0129x over previous
.LBB0_878:
	s_or_b64 exec, exec, s[4:5]
	s_lshl_b32 s4, s12, 5
	v_and_b32_e32 v49, 15, v48
	s_lshl_b32 s5, s17, 9
	s_and_b32 s6, s4, 0x180
	s_lshl_b32 s4, s11, 4
	s_waitcnt lgkmcnt(1)
	v_or_b32_e32 v5, s4, v49
	s_or_b32 s5, s6, s5
	s_lshl_b32 s0, s17, 10
	s_lshl_b32 s1, s12, 6
	v_add_u32_e32 v8, s5, v5
	s_or_b32 s0, s1, s0
	v_ashrrev_i32_e32 v9, 31, v8
	v_readlane_b32 s6, v252, 41
	v_lshrrev_b32_e32 v55, 4, v4
	s_ashr_i32 s1, s0, 31
	v_lshlrev_b64 v[8:9], 12, v[8:9]
	v_readlane_b32 s7, v252, 42
	v_lshl_or_b32 v0, s11, 3, v55
	s_lshl_b64 s[0:1], s[0:1], 12
	v_lshl_add_u64 v[8:9], s[6:7], 0, v[8:9]
	v_readlane_b32 s6, v252, 38
	v_ashrrev_i32_e32 v1, 31, v0
	v_or_b32_e32 v6, 4, v0
	v_readlane_b32 s7, v252, 39
	s_add_u32 s0, s6, s0
	v_lshlrev_b64 v[2:3], 12, v[0:1]
	v_bitop3_b32 v1, v0, v49, 11 bitop3:0x6c
	v_ashrrev_i32_e32 v7, 31, v6
	s_addc_u32 s1, s7, s1
	v_lshlrev_b32_e32 v144, 4, v1
	v_lshlrev_b64 v[6:7], 12, v[6:7]
	v_lshl_add_u64 v[2:3], s[0:1], 0, v[2:3]
	v_lshl_add_u64 v[98:99], v[2:3], 0, v[144:145]
	v_lshl_add_u64 v[2:3], s[0:1], 0, v[6:7]
	s_and_b64 s[0:1], s[2:3], exec
	v_bitop3_b32 v0, v0, v48, 4 bitop3:0x36
	s_cselect_b32 s24, 0, 0xf00
	s_lshl_b32 s0, s11, 11
	v_lshlrev_b32_e32 v0, 4, v0
	s_add_i32 s6, s0, 16
	v_and_b32_e32 v0, 0xf0, v0
	v_mov_b32_e32 v1, v145
	s_add_i32 s7, s6, 0x400
	v_and_b32_e32 v4, 48, v4
	v_mov_b32_e32 v5, v145
	v_lshl_add_u64 v[100:101], v[2:3], 0, v[0:1]
	v_lshl_add_u64 v[0:1], v[98:99], 0, s[24:25]
	s_mov_b32 m0, s6
	s_and_b64 s[0:1], s[2:3], exec
	s_waitcnt lgkmcnt(0)
	s_barrier
	v_lshl_add_u64 v[96:97], v[8:9], 0, v[4:5]
	global_load_lds_dwordx4 v[0:1], off
	v_lshl_add_u64 v[0:1], v[100:101], 0, s[24:25]
	s_mov_b32 m0, s7
	s_movk_i32 s0, 0xe00
	global_load_lds_dwordx4 v[0:1], off
	v_lshl_add_u64 v[16:17], v[96:97], 0, s[24:25]
	s_cselect_b32 s24, 0x100, s0
	s_add_i32 s8, s6, 0x4000
	s_add_i32 s9, s6, 0x4400
	global_load_dwordx4 v[12:15], v[16:17], off
	global_load_dwordx4 v[8:11], v[16:17], off offset:64
	global_load_dwordx4 v[4:7], v[16:17], off offset:128
	global_load_dwordx4 v[0:3], v[16:17], off offset:192
	v_lshl_add_u64 v[16:17], v[98:99], 0, s[24:25]
	s_mov_b32 m0, s8
	s_and_b64 s[0:1], s[2:3], exec
	global_load_lds_dwordx4 v[16:17], off
	v_lshl_add_u64 v[16:17], v[100:101], 0, s[24:25]
	s_mov_b32 m0, s9
	s_movk_i32 s0, 0xd00
	global_load_lds_dwordx4 v[16:17], off
	v_lshl_add_u64 v[32:33], v[96:97], 0, s[24:25]
	s_cselect_b32 s24, 0x200, s0
	s_add_i32 s11, s6, 0x8000
	global_load_dwordx4 v[28:31], v[32:33], off
	global_load_dwordx4 v[24:27], v[32:33], off offset:64
	global_load_dwordx4 v[20:23], v[32:33], off offset:128
	global_load_dwordx4 v[16:19], v[32:33], off offset:192
	v_lshl_add_u64 v[32:33], v[98:99], 0, s[24:25]
	s_mov_b32 m0, s11
	s_add_i32 s12, s6, 0x8400
	global_load_lds_dwordx4 v[32:33], off
	v_lshl_add_u64 v[32:33], v[100:101], 0, s[24:25]
	s_mov_b32 m0, s12
	s_ashr_i32 s5, s4, 31
	global_load_lds_dwordx4 v[32:33], off
	s_lshl_b32 s17, s17, 4
	s_and_b32 s18, s18, 31
	s_lshl_b64 s[0:1], s[4:5], 1
	v_readlane_b32 s4, v252, 17
	s_add_u32 s0, s4, s0
	v_readlane_b32 s4, v252, 18
	v_lshlrev_b32_e32 v50, 3, v55
	v_mov_b32_e32 v51, v145
	v_lshl_add_u64 v[52:53], v[96:97], 0, s[24:25]
	s_addc_u32 s1, s4, s1
	global_load_dwordx4 v[44:47], v[52:53], off
	global_load_dwordx4 v[40:43], v[52:53], off offset:64
	global_load_dwordx4 v[36:39], v[52:53], off offset:128
	global_load_dwordx4 v[32:35], v[52:53], off offset:192
	v_lshlrev_b32_e32 v102, 7, v49
	v_lshl_add_u64 v[104:105], s[0:1], 0, v[50:51]
	v_lshl_add_u32 v51, v49, 8, 16
	v_bitop3_b32 v48, v55, v48, 15 bitop3:0x78
	v_bitop3_b32 v53, v55, v49, 4 bitop3:0x36
	v_bitop3_b32 v56, v55, v49, 8 bitop3:0x36
	v_bitop3_b32 v49, v55, v49, 12 bitop3:0x36
	v_or_b32_e32 v50, 0x800, v102
	v_or_b32_e32 v52, 0x1000, v102
	v_or_b32_e32 v54, 0x1800, v102
	v_lshlrev_b32_e32 v48, 4, v48
	v_lshlrev_b32_e32 v53, 4, v53
	v_lshlrev_b32_e32 v56, 4, v56
	v_lshlrev_b32_e32 v49, 4, v49
	v_mov_b32_e32 v92, 0
	s_mov_b32 s13, 6
	s_mov_b32 s16, 9
	v_lshl_add_u32 v103, v55, 5, s71
	v_lshlrev_b32_e32 v106, 1, v50
	v_lshlrev_b32_e32 v108, 1, v52
	v_lshlrev_b32_e32 v110, 1, v54
	v_add_u32_e32 v112, v51, v48
	v_add_u32_e32 v113, v51, v53
	v_add_u32_e32 v114, v51, v56
	v_add_u32_e32 v115, v51, v49
	v_mov_b32_e32 v93, v92
	v_mov_b32_e32 v94, v92
	v_mov_b32_e32 v95, v92
	v_mov_b32_e32 v88, v92
	v_mov_b32_e32 v89, v92
	v_mov_b32_e32 v90, v92
	v_mov_b32_e32 v91, v92
	v_mov_b32_e32 v84, v92
	v_mov_b32_e32 v85, v92
	v_mov_b32_e32 v86, v92
	v_mov_b32_e32 v87, v92
	v_mov_b32_e32 v80, v92
	v_mov_b32_e32 v81, v92
	v_mov_b32_e32 v82, v92
	v_mov_b32_e32 v83, v92
	s_and_b64 s[0:1], s[2:3], exec
	s_cselect_b32 s20, 0, 15
	s_cselect_b32 s21, 1, -1
	s_mov_b32 s19, 0
	v_mov_b32_e32 v107, 0
	v_mov_b32_e32 v109, 0
	v_mov_b32_e32 v111, 0
	v_lshlrev_b32_e32 v144, 1, v102
	v_mov_b32_e32 v80, 0
	v_mov_b32_e32 v81, 0
	v_mov_b32_e32 v82, 0
	v_mov_b32_e32 v83, 0
	v_mov_b32_e32 v84, 0
	v_mov_b32_e32 v85, 0
	v_mov_b32_e32 v86, 0
	v_mov_b32_e32 v87, 0
	v_mov_b32_e32 v88, 0
	v_mov_b32_e32 v89, 0
	v_mov_b32_e32 v90, 0
	v_mov_b32_e32 v91, 0
	v_mov_b32_e32 v92, 0
	v_mov_b32_e32 v93, 0
	v_mov_b32_e32 v94, 0
	v_mov_b32_e32 v95, 0
.Lsc_loop:
	s_mul_i32 s0, s21, 3
	s_add_i32 s0, s20, s0
	s_lshl_b32 s24, s0, 8
	s_add_i32 s4, s6, 0xc000
	s_mov_b32 m0, s4
	v_lshl_add_u64 v[116:117], v[98:99], 0, s[24:25]
	v_lshl_add_u64 v[118:119], v[100:101], 0, s[24:25]
	global_load_lds_dwordx4 v[116:117], off
	s_add_i32 s4, s4, 0x400
	s_mov_b32 m0, s4
	v_lshl_add_u64 v[120:121], v[96:97], 0, s[24:25]
	global_load_lds_dwordx4 v[118:119], off
	global_load_dwordx4 v[60:63], v[120:121], off
	global_load_dwordx4 v[56:59], v[120:121], off offset:64
	global_load_dwordx4 v[52:55], v[120:121], off offset:128
	global_load_dwordx4 v[48:51], v[120:121], off offset:192
	s_cmp_eq_u32 s19, 0
	s_cbranch_scc1 .Lsc_wf0
	s_waitcnt vmcnt(30)
	s_branch .Lsc_wd0
.Lsc_wf0:
	s_waitcnt vmcnt(18)
.Lsc_wd0:
	s_barrier
	s_lshl_b32 s0, s20, 2
	s_add_i32 s0, s0, 0x12010
	v_mov_b32_e32 v116, s0
	v_lshl_add_u32 v132, s20, 9, v103
	ds_read_b32 v218, v116
	ds_read_b128 v[178:181], v132
	ds_read_b128 v[182:185], v132 offset:16
	ds_read_b128 v[146:149], v112
	ds_read_b128 v[150:153], v112 offset:4096
	ds_read_b128 v[154:157], v112 offset:8192
	ds_read_b128 v[158:161], v112 offset:12288
	ds_read_b128 v[186:189], v132 offset:128
	ds_read_b128 v[190:193], v132 offset:144
	ds_read_b128 v[162:165], v113
	ds_read_b128 v[166:169], v113 offset:4096
	ds_read_b128 v[170:173], v113 offset:8192
	ds_read_b128 v[174:177], v113 offset:12288
	s_add_i32 s0, s20, s17
	s_lshl_b32 s0, s0, 5
	s_or_b32 s0, s0, s18
	s_ashr_i32 s1, s0, 31
	s_lshl_b64 s[0:1], s[0:1], 14
	v_lshl_add_u64 v[118:119], v[104:105], 0, s[0:1]
	v_cvt_pk_bf16_f32 v134, v80, v81
	v_cvt_pk_bf16_f32 v135, v82, v83
	v_lshl_add_u64 v[122:123], v[118:119], 0, v[144:145]
	v_cvt_pk_bf16_f32 v136, v84, v85
	v_cvt_pk_bf16_f32 v137, v86, v87
	v_lshl_add_u64 v[124:125], v[118:119], 0, v[106:107]
	v_cvt_pk_bf16_f32 v138, v88, v89
	v_cvt_pk_bf16_f32 v139, v90, v91
	v_lshl_add_u64 v[126:127], v[118:119], 0, v[108:109]
	v_cvt_pk_bf16_f32 v140, v92, v93
	v_cvt_pk_bf16_f32 v141, v94, v95
	v_lshl_add_u64 v[128:129], v[118:119], 0, v[110:111]
	global_store_dwordx2 v[122:123], v[134:135], off
	global_store_dwordx2 v[124:125], v[136:137], off
	global_store_dwordx2 v[126:127], v[138:139], off
	global_store_dwordx2 v[128:129], v[140:141], off
	s_waitcnt lgkmcnt(12)
	v_pk_mul_f32 v[80:81], v[80:81], v[218:219] op_sel_hi:[1,0]
	v_pk_mul_f32 v[82:83], v[82:83], v[218:219] op_sel_hi:[1,0]
	v_pk_mul_f32 v[84:85], v[84:85], v[218:219] op_sel_hi:[1,0]
	v_pk_mul_f32 v[86:87], v[86:87], v[218:219] op_sel_hi:[1,0]
	v_pk_mul_f32 v[88:89], v[88:89], v[218:219] op_sel_hi:[1,0]
	v_pk_mul_f32 v[90:91], v[90:91], v[218:219] op_sel_hi:[1,0]
	v_pk_mul_f32 v[92:93], v[92:93], v[218:219] op_sel_hi:[1,0]
	v_pk_mul_f32 v[94:95], v[94:95], v[218:219] op_sel_hi:[1,0]
	v_lshlrev_b32_e32 v194, 16, v12
	v_and_b32_e32 v195, 0xffff0000, v12
	v_lshlrev_b32_e32 v196, 16, v13
	v_and_b32_e32 v197, 0xffff0000, v13
	v_lshlrev_b32_e32 v198, 16, v14
	v_and_b32_e32 v199, 0xffff0000, v14
	v_lshlrev_b32_e32 v200, 16, v15
	v_and_b32_e32 v201, 0xffff0000, v15
	s_waitcnt lgkmcnt(10)
	v_pk_mul_f32 v[194:195], v[178:179], v[194:195]
	v_pk_mul_f32 v[196:197], v[180:181], v[196:197]
	v_pk_mul_f32 v[198:199], v[182:183], v[198:199]
	v_pk_mul_f32 v[200:201], v[184:185], v[200:201]
	v_cvt_pk_bf16_f32 v12, v194, v195
	v_cvt_pk_bf16_f32 v13, v196, v197
	v_cvt_pk_bf16_f32 v14, v198, v199
	v_cvt_pk_bf16_f32 v15, v200, v201
	s_nop 1
	s_waitcnt lgkmcnt(9)
	v_mfma_f32_16x16x32_bf16 v[80:83], v[12:15], v[146:149], v[80:83]
	v_lshlrev_b32_e32 v202, 16, v8
	v_and_b32_e32 v203, 0xffff0000, v8
	s_waitcnt lgkmcnt(8)
	v_mfma_f32_16x16x32_bf16 v[84:87], v[12:15], v[150:153], v[84:87]
	v_lshlrev_b32_e32 v204, 16, v9
	v_and_b32_e32 v205, 0xffff0000, v9
	s_waitcnt lgkmcnt(7)
	v_mfma_f32_16x16x32_bf16 v[88:91], v[12:15], v[154:157], v[88:91]
	v_lshlrev_b32_e32 v206, 16, v10
	v_and_b32_e32 v207, 0xffff0000, v10
	s_waitcnt lgkmcnt(6)
	v_mfma_f32_16x16x32_bf16 v[92:95], v[12:15], v[158:161], v[92:95]
	v_lshlrev_b32_e32 v208, 16, v11
	v_and_b32_e32 v209, 0xffff0000, v11
	ds_read_b128 v[178:181], v132 offset:256
	ds_read_b128 v[182:185], v132 offset:272
	ds_read_b128 v[146:149], v114
	ds_read_b128 v[150:153], v114 offset:4096
	ds_read_b128 v[154:157], v114 offset:8192
	ds_read_b128 v[158:161], v114 offset:12288
	s_waitcnt lgkmcnt(10)
	v_pk_mul_f32 v[202:203], v[186:187], v[202:203]
	v_pk_mul_f32 v[204:205], v[188:189], v[204:205]
	v_pk_mul_f32 v[206:207], v[190:191], v[206:207]
	v_pk_mul_f32 v[208:209], v[192:193], v[208:209]
	v_cvt_pk_bf16_f32 v8, v202, v203
	v_cvt_pk_bf16_f32 v9, v204, v205
	v_cvt_pk_bf16_f32 v10, v206, v207
	v_cvt_pk_bf16_f32 v11, v208, v209
	s_nop 1
	s_waitcnt lgkmcnt(9)
	v_mfma_f32_16x16x32_bf16 v[80:83], v[8:11], v[162:165], v[80:83]
	v_lshlrev_b32_e32 v194, 16, v4
	v_and_b32_e32 v195, 0xffff0000, v4
	s_waitcnt lgkmcnt(8)
	v_mfma_f32_16x16x32_bf16 v[84:87], v[8:11], v[166:169], v[84:87]
	v_lshlrev_b32_e32 v196, 16, v5
	v_and_b32_e32 v197, 0xffff0000, v5
	s_waitcnt lgkmcnt(7)
	v_mfma_f32_16x16x32_bf16 v[88:91], v[8:11], v[170:173], v[88:91]
	v_lshlrev_b32_e32 v198, 16, v6
	v_and_b32_e32 v199, 0xffff0000, v6
	s_waitcnt lgkmcnt(6)
	v_mfma_f32_16x16x32_bf16 v[92:95], v[8:11], v[174:177], v[92:95]
	v_lshlrev_b32_e32 v200, 16, v7
	v_and_b32_e32 v201, 0xffff0000, v7
	ds_read_b128 v[186:189], v132 offset:384
	ds_read_b128 v[190:193], v132 offset:400
	ds_read_b128 v[162:165], v115
	ds_read_b128 v[166:169], v115 offset:4096
	ds_read_b128 v[170:173], v115 offset:8192
	ds_read_b128 v[174:177], v115 offset:12288
	s_waitcnt lgkmcnt(10)
	v_pk_mul_f32 v[194:195], v[178:179], v[194:195]
	v_pk_mul_f32 v[196:197], v[180:181], v[196:197]
	v_pk_mul_f32 v[198:199], v[182:183], v[198:199]
	v_pk_mul_f32 v[200:201], v[184:185], v[200:201]
	v_cvt_pk_bf16_f32 v4, v194, v195
	v_cvt_pk_bf16_f32 v5, v196, v197
	v_cvt_pk_bf16_f32 v6, v198, v199
	v_cvt_pk_bf16_f32 v7, v200, v201
	s_nop 1
	s_waitcnt lgkmcnt(9)
	v_mfma_f32_16x16x32_bf16 v[80:83], v[4:7], v[146:149], v[80:83]
	v_lshlrev_b32_e32 v202, 16, v0
	v_and_b32_e32 v203, 0xffff0000, v0
	s_waitcnt lgkmcnt(8)
	v_mfma_f32_16x16x32_bf16 v[84:87], v[4:7], v[150:153], v[84:87]
	v_lshlrev_b32_e32 v204, 16, v1
	v_and_b32_e32 v205, 0xffff0000, v1
	s_waitcnt lgkmcnt(7)
	v_mfma_f32_16x16x32_bf16 v[88:91], v[4:7], v[154:157], v[88:91]
	v_lshlrev_b32_e32 v206, 16, v2
	v_and_b32_e32 v207, 0xffff0000, v2
	s_waitcnt lgkmcnt(6)
	v_mfma_f32_16x16x32_bf16 v[92:95], v[4:7], v[158:161], v[92:95]
	v_lshlrev_b32_e32 v208, 16, v3
	v_and_b32_e32 v209, 0xffff0000, v3
	s_waitcnt lgkmcnt(4)
	v_pk_mul_f32 v[202:203], v[186:187], v[202:203]
	v_pk_mul_f32 v[204:205], v[188:189], v[204:205]
	v_pk_mul_f32 v[206:207], v[190:191], v[206:207]
	v_pk_mul_f32 v[208:209], v[192:193], v[208:209]
	v_cvt_pk_bf16_f32 v0, v202, v203
	v_cvt_pk_bf16_f32 v1, v204, v205
	v_cvt_pk_bf16_f32 v2, v206, v207
	v_cvt_pk_bf16_f32 v3, v208, v209
	s_nop 1
	s_waitcnt lgkmcnt(3)
	v_mfma_f32_16x16x32_bf16 v[80:83], v[0:3], v[162:165], v[80:83]
	s_waitcnt lgkmcnt(2)
	v_mfma_f32_16x16x32_bf16 v[84:87], v[0:3], v[166:169], v[84:87]
	s_waitcnt lgkmcnt(1)
	v_mfma_f32_16x16x32_bf16 v[88:91], v[0:3], v[170:173], v[88:91]
	s_waitcnt lgkmcnt(0)
	v_mfma_f32_16x16x32_bf16 v[92:95], v[0:3], v[174:177], v[92:95]
	s_add_i32 s20, s20, s21
	s_barrier
	s_cmp_eq_u32 s19, 12
	s_cbranch_scc1 .Lsc_noiss1
	s_mul_i32 s0, s21, 3
	s_add_i32 s0, s20, s0
	s_lshl_b32 s24, s0, 8
	s_add_i32 s4, s6, 0x0
	s_mov_b32 m0, s4
	v_lshl_add_u64 v[116:117], v[98:99], 0, s[24:25]
	v_lshl_add_u64 v[118:119], v[100:101], 0, s[24:25]
	global_load_lds_dwordx4 v[116:117], off
	s_add_i32 s4, s4, 0x400
	s_mov_b32 m0, s4
	v_lshl_add_u64 v[120:121], v[96:97], 0, s[24:25]
	global_load_lds_dwordx4 v[118:119], off
	global_load_dwordx4 v[12:15], v[120:121], off
	global_load_dwordx4 v[8:11], v[120:121], off offset:64
	global_load_dwordx4 v[4:7], v[120:121], off offset:128
	global_load_dwordx4 v[0:3], v[120:121], off offset:192
.Lsc_noiss1:
	s_cmp_eq_u32 s19, 0
	s_cbranch_scc1 .Lsc_wf1
	s_cmp_eq_u32 s19, 12
	s_cbranch_scc1 .Lsc_wl1
	s_waitcnt vmcnt(30)
	s_branch .Lsc_wd1
.Lsc_wf1:
	s_waitcnt vmcnt(22)
	s_branch .Lsc_wd1
.Lsc_wl1:
	s_waitcnt vmcnt(24)
.Lsc_wd1:
	s_barrier
	s_lshl_b32 s0, s20, 2
	s_add_i32 s0, s0, 0x12010
	v_mov_b32_e32 v116, s0
	v_lshl_add_u32 v132, s20, 9, v103
	ds_read_b32 v218, v116
	ds_read_b128 v[178:181], v132
	ds_read_b128 v[182:185], v132 offset:16
	ds_read_b128 v[146:149], v112 offset:16384
	ds_read_b128 v[150:153], v112 offset:20480
	ds_read_b128 v[154:157], v112 offset:24576
	ds_read_b128 v[158:161], v112 offset:28672
	ds_read_b128 v[186:189], v132 offset:128
	ds_read_b128 v[190:193], v132 offset:144
	ds_read_b128 v[162:165], v113 offset:16384
	ds_read_b128 v[166:169], v113 offset:20480
	ds_read_b128 v[170:173], v113 offset:24576
	ds_read_b128 v[174:177], v113 offset:28672
	s_add_i32 s0, s20, s17
	s_lshl_b32 s0, s0, 5
	s_or_b32 s0, s0, s18
	s_ashr_i32 s1, s0, 31
	s_lshl_b64 s[0:1], s[0:1], 14
	v_lshl_add_u64 v[118:119], v[104:105], 0, s[0:1]
	v_cvt_pk_bf16_f32 v134, v80, v81
	v_cvt_pk_bf16_f32 v135, v82, v83
	v_lshl_add_u64 v[122:123], v[118:119], 0, v[144:145]
	v_cvt_pk_bf16_f32 v136, v84, v85
	v_cvt_pk_bf16_f32 v137, v86, v87
	v_lshl_add_u64 v[124:125], v[118:119], 0, v[106:107]
	v_cvt_pk_bf16_f32 v138, v88, v89
	v_cvt_pk_bf16_f32 v139, v90, v91
	v_lshl_add_u64 v[126:127], v[118:119], 0, v[108:109]
	v_cvt_pk_bf16_f32 v140, v92, v93
	v_cvt_pk_bf16_f32 v141, v94, v95
	v_lshl_add_u64 v[128:129], v[118:119], 0, v[110:111]
	global_store_dwordx2 v[122:123], v[134:135], off
	global_store_dwordx2 v[124:125], v[136:137], off
	global_store_dwordx2 v[126:127], v[138:139], off
	global_store_dwordx2 v[128:129], v[140:141], off
	s_waitcnt lgkmcnt(12)
	v_pk_mul_f32 v[80:81], v[80:81], v[218:219] op_sel_hi:[1,0]
	v_pk_mul_f32 v[82:83], v[82:83], v[218:219] op_sel_hi:[1,0]
	v_pk_mul_f32 v[84:85], v[84:85], v[218:219] op_sel_hi:[1,0]
	v_pk_mul_f32 v[86:87], v[86:87], v[218:219] op_sel_hi:[1,0]
	v_pk_mul_f32 v[88:89], v[88:89], v[218:219] op_sel_hi:[1,0]
	v_pk_mul_f32 v[90:91], v[90:91], v[218:219] op_sel_hi:[1,0]
	v_pk_mul_f32 v[92:93], v[92:93], v[218:219] op_sel_hi:[1,0]
	v_pk_mul_f32 v[94:95], v[94:95], v[218:219] op_sel_hi:[1,0]
	v_lshlrev_b32_e32 v194, 16, v28
	v_and_b32_e32 v195, 0xffff0000, v28
	v_lshlrev_b32_e32 v196, 16, v29
	v_and_b32_e32 v197, 0xffff0000, v29
	v_lshlrev_b32_e32 v198, 16, v30
	v_and_b32_e32 v199, 0xffff0000, v30
	v_lshlrev_b32_e32 v200, 16, v31
	v_and_b32_e32 v201, 0xffff0000, v31
	s_waitcnt lgkmcnt(10)
	v_pk_mul_f32 v[194:195], v[178:179], v[194:195]
	v_pk_mul_f32 v[196:197], v[180:181], v[196:197]
	v_pk_mul_f32 v[198:199], v[182:183], v[198:199]
	v_pk_mul_f32 v[200:201], v[184:185], v[200:201]
	v_cvt_pk_bf16_f32 v28, v194, v195
	v_cvt_pk_bf16_f32 v29, v196, v197
	v_cvt_pk_bf16_f32 v30, v198, v199
	v_cvt_pk_bf16_f32 v31, v200, v201
	s_nop 1
	s_waitcnt lgkmcnt(9)
	v_mfma_f32_16x16x32_bf16 v[80:83], v[28:31], v[146:149], v[80:83]
	v_lshlrev_b32_e32 v202, 16, v24
	v_and_b32_e32 v203, 0xffff0000, v24
	s_waitcnt lgkmcnt(8)
	v_mfma_f32_16x16x32_bf16 v[84:87], v[28:31], v[150:153], v[84:87]
	v_lshlrev_b32_e32 v204, 16, v25
	v_and_b32_e32 v205, 0xffff0000, v25
	s_waitcnt lgkmcnt(7)
	v_mfma_f32_16x16x32_bf16 v[88:91], v[28:31], v[154:157], v[88:91]
	v_lshlrev_b32_e32 v206, 16, v26
	v_and_b32_e32 v207, 0xffff0000, v26
	s_waitcnt lgkmcnt(6)
	v_mfma_f32_16x16x32_bf16 v[92:95], v[28:31], v[158:161], v[92:95]
	v_lshlrev_b32_e32 v208, 16, v27
	v_and_b32_e32 v209, 0xffff0000, v27
	ds_read_b128 v[178:181], v132 offset:256
	ds_read_b128 v[182:185], v132 offset:272
	ds_read_b128 v[146:149], v114 offset:16384
	ds_read_b128 v[150:153], v114 offset:20480
	ds_read_b128 v[154:157], v114 offset:24576
	ds_read_b128 v[158:161], v114 offset:28672
	s_waitcnt lgkmcnt(10)
	v_pk_mul_f32 v[202:203], v[186:187], v[202:203]
	v_pk_mul_f32 v[204:205], v[188:189], v[204:205]
	v_pk_mul_f32 v[206:207], v[190:191], v[206:207]
	v_pk_mul_f32 v[208:209], v[192:193], v[208:209]
	v_cvt_pk_bf16_f32 v24, v202, v203
	v_cvt_pk_bf16_f32 v25, v204, v205
	v_cvt_pk_bf16_f32 v26, v206, v207
	v_cvt_pk_bf16_f32 v27, v208, v209
	s_nop 1
	s_waitcnt lgkmcnt(9)
	v_mfma_f32_16x16x32_bf16 v[80:83], v[24:27], v[162:165], v[80:83]
	v_lshlrev_b32_e32 v194, 16, v20
	v_and_b32_e32 v195, 0xffff0000, v20
	s_waitcnt lgkmcnt(8)
	v_mfma_f32_16x16x32_bf16 v[84:87], v[24:27], v[166:169], v[84:87]
	v_lshlrev_b32_e32 v196, 16, v21
	v_and_b32_e32 v197, 0xffff0000, v21
	s_waitcnt lgkmcnt(7)
	v_mfma_f32_16x16x32_bf16 v[88:91], v[24:27], v[170:173], v[88:91]
	v_lshlrev_b32_e32 v198, 16, v22
	v_and_b32_e32 v199, 0xffff0000, v22
	s_waitcnt lgkmcnt(6)
	v_mfma_f32_16x16x32_bf16 v[92:95], v[24:27], v[174:177], v[92:95]
	v_lshlrev_b32_e32 v200, 16, v23
	v_and_b32_e32 v201, 0xffff0000, v23
	ds_read_b128 v[186:189], v132 offset:384
	ds_read_b128 v[190:193], v132 offset:400
	ds_read_b128 v[162:165], v115 offset:16384
	ds_read_b128 v[166:169], v115 offset:20480
	ds_read_b128 v[170:173], v115 offset:24576
	ds_read_b128 v[174:177], v115 offset:28672
	s_waitcnt lgkmcnt(10)
	v_pk_mul_f32 v[194:195], v[178:179], v[194:195]
	v_pk_mul_f32 v[196:197], v[180:181], v[196:197]
	v_pk_mul_f32 v[198:199], v[182:183], v[198:199]
	v_pk_mul_f32 v[200:201], v[184:185], v[200:201]
	v_cvt_pk_bf16_f32 v20, v194, v195
	v_cvt_pk_bf16_f32 v21, v196, v197
	v_cvt_pk_bf16_f32 v22, v198, v199
	v_cvt_pk_bf16_f32 v23, v200, v201
	s_nop 1
	s_waitcnt lgkmcnt(9)
	v_mfma_f32_16x16x32_bf16 v[80:83], v[20:23], v[146:149], v[80:83]
	v_lshlrev_b32_e32 v202, 16, v16
	v_and_b32_e32 v203, 0xffff0000, v16
	s_waitcnt lgkmcnt(8)
	v_mfma_f32_16x16x32_bf16 v[84:87], v[20:23], v[150:153], v[84:87]
	v_lshlrev_b32_e32 v204, 16, v17
	v_and_b32_e32 v205, 0xffff0000, v17
	s_waitcnt lgkmcnt(7)
	v_mfma_f32_16x16x32_bf16 v[88:91], v[20:23], v[154:157], v[88:91]
	v_lshlrev_b32_e32 v206, 16, v18
	v_and_b32_e32 v207, 0xffff0000, v18
	s_waitcnt lgkmcnt(6)
	v_mfma_f32_16x16x32_bf16 v[92:95], v[20:23], v[158:161], v[92:95]
	v_lshlrev_b32_e32 v208, 16, v19
	v_and_b32_e32 v209, 0xffff0000, v19
	s_waitcnt lgkmcnt(4)
	v_pk_mul_f32 v[202:203], v[186:187], v[202:203]
	v_pk_mul_f32 v[204:205], v[188:189], v[204:205]
	v_pk_mul_f32 v[206:207], v[190:191], v[206:207]
	v_pk_mul_f32 v[208:209], v[192:193], v[208:209]
	v_cvt_pk_bf16_f32 v16, v202, v203
	v_cvt_pk_bf16_f32 v17, v204, v205
	v_cvt_pk_bf16_f32 v18, v206, v207
	v_cvt_pk_bf16_f32 v19, v208, v209
	s_nop 1
	s_waitcnt lgkmcnt(3)
	v_mfma_f32_16x16x32_bf16 v[80:83], v[16:19], v[162:165], v[80:83]
	s_waitcnt lgkmcnt(2)
	v_mfma_f32_16x16x32_bf16 v[84:87], v[16:19], v[166:169], v[84:87]
	s_waitcnt lgkmcnt(1)
	v_mfma_f32_16x16x32_bf16 v[88:91], v[16:19], v[170:173], v[88:91]
	s_waitcnt lgkmcnt(0)
	v_mfma_f32_16x16x32_bf16 v[92:95], v[16:19], v[174:177], v[92:95]
	s_add_i32 s20, s20, s21
	s_barrier
	s_cmp_eq_u32 s19, 12
	s_cbranch_scc1 .Lsc_noiss2
	s_mul_i32 s0, s21, 3
	s_add_i32 s0, s20, s0
	s_lshl_b32 s24, s0, 8
	s_add_i32 s4, s6, 0x4000
	s_mov_b32 m0, s4
	v_lshl_add_u64 v[116:117], v[98:99], 0, s[24:25]
	v_lshl_add_u64 v[118:119], v[100:101], 0, s[24:25]
	global_load_lds_dwordx4 v[116:117], off
	s_add_i32 s4, s4, 0x400
	s_mov_b32 m0, s4
	v_lshl_add_u64 v[120:121], v[96:97], 0, s[24:25]
	global_load_lds_dwordx4 v[118:119], off
	global_load_dwordx4 v[28:31], v[120:121], off
	global_load_dwordx4 v[24:27], v[120:121], off offset:64
	global_load_dwordx4 v[20:23], v[120:121], off offset:128
	global_load_dwordx4 v[16:19], v[120:121], off offset:192

.Lsc_wf2:
	s_waitcnt vmcnt(26)
	s_branch .Lsc_wd2

.Lsc_wd2:
	s_barrier
	s_lshl_b32 s0, s20, 2
	s_add_i32 s0, s0, 0x12010
	v_mov_b32_e32 v116, s0
	v_lshl_add_u32 v132, s20, 9, v103
	ds_read_b32 v218, v116
	ds_read_b128 v[178:181], v132
	ds_read_b128 v[182:185], v132 offset:16
	ds_read_b128 v[146:149], v112 offset:32768
	ds_read_b128 v[150:153], v112 offset:36864
	ds_read_b128 v[154:157], v112 offset:40960
	ds_read_b128 v[158:161], v112 offset:45056
	ds_read_b128 v[186:189], v132 offset:128
	ds_read_b128 v[190:193], v132 offset:144
	ds_read_b128 v[162:165], v113 offset:32768
	ds_read_b128 v[166:169], v113 offset:36864
	ds_read_b128 v[170:173], v113 offset:40960
	ds_read_b128 v[174:177], v113 offset:45056
	s_add_i32 s0, s20, s17
	s_lshl_b32 s0, s0, 5
	s_or_b32 s0, s0, s18
	s_ashr_i32 s1, s0, 31
	s_lshl_b64 s[0:1], s[0:1], 14
	v_lshl_add_u64 v[118:119], v[104:105], 0, s[0:1]
	v_cvt_pk_bf16_f32 v134, v80, v81
	v_cvt_pk_bf16_f32 v135, v82, v83
	v_lshl_add_u64 v[122:123], v[118:119], 0, v[144:145]
	v_cvt_pk_bf16_f32 v136, v84, v85
	v_cvt_pk_bf16_f32 v137, v86, v87
	v_lshl_add_u64 v[124:125], v[118:119], 0, v[106:107]
	v_cvt_pk_bf16_f32 v138, v88, v89
	v_cvt_pk_bf16_f32 v139, v90, v91
	v_lshl_add_u64 v[126:127], v[118:119], 0, v[108:109]
	v_cvt_pk_bf16_f32 v140, v92, v93
	v_cvt_pk_bf16_f32 v141, v94, v95
	v_lshl_add_u64 v[128:129], v[118:119], 0, v[110:111]
	global_store_dwordx2 v[122:123], v[134:135], off
	global_store_dwordx2 v[124:125], v[136:137], off
	global_store_dwordx2 v[126:127], v[138:139], off
	global_store_dwordx2 v[128:129], v[140:141], off
	s_waitcnt lgkmcnt(12)
	v_pk_mul_f32 v[80:81], v[80:81], v[218:219] op_sel_hi:[1,0]
	v_pk_mul_f32 v[82:83], v[82:83], v[218:219] op_sel_hi:[1,0]
	v_pk_mul_f32 v[84:85], v[84:85], v[218:219] op_sel_hi:[1,0]
	v_pk_mul_f32 v[86:87], v[86:87], v[218:219] op_sel_hi:[1,0]
	v_pk_mul_f32 v[88:89], v[88:89], v[218:219] op_sel_hi:[1,0]
	v_pk_mul_f32 v[90:91], v[90:91], v[218:219] op_sel_hi:[1,0]
	v_pk_mul_f32 v[92:93], v[92:93], v[218:219] op_sel_hi:[1,0]
	v_pk_mul_f32 v[94:95], v[94:95], v[218:219] op_sel_hi:[1,0]
	v_lshlrev_b32_e32 v194, 16, v44
	v_and_b32_e32 v195, 0xffff0000, v44
	v_lshlrev_b32_e32 v196, 16, v45
	v_and_b32_e32 v197, 0xffff0000, v45
	v_lshlrev_b32_e32 v198, 16, v46
	v_and_b32_e32 v199, 0xffff0000, v46
	v_lshlrev_b32_e32 v200, 16, v47
	v_and_b32_e32 v201, 0xffff0000, v47
	s_waitcnt lgkmcnt(10)
	v_pk_mul_f32 v[194:195], v[178:179], v[194:195]
	v_pk_mul_f32 v[196:197], v[180:181], v[196:197]
	v_pk_mul_f32 v[198:199], v[182:183], v[198:199]
	v_pk_mul_f32 v[200:201], v[184:185], v[200:201]
	v_cvt_pk_bf16_f32 v44, v194, v195
	v_cvt_pk_bf16_f32 v45, v196, v197
	v_cvt_pk_bf16_f32 v46, v198, v199
	v_cvt_pk_bf16_f32 v47, v200, v201
	s_nop 1
	s_waitcnt lgkmcnt(9)
	v_mfma_f32_16x16x32_bf16 v[80:83], v[44:47], v[146:149], v[80:83]
	v_lshlrev_b32_e32 v202, 16, v40
	v_and_b32_e32 v203, 0xffff0000, v40
	s_waitcnt lgkmcnt(8)
	v_mfma_f32_16x16x32_bf16 v[84:87], v[44:47], v[150:153], v[84:87]
	v_lshlrev_b32_e32 v204, 16, v41
	v_and_b32_e32 v205, 0xffff0000, v41
	s_waitcnt lgkmcnt(7)
	v_mfma_f32_16x16x32_bf16 v[88:91], v[44:47], v[154:157], v[88:91]
	v_lshlrev_b32_e32 v206, 16, v42
	v_and_b32_e32 v207, 0xffff0000, v42
	s_waitcnt lgkmcnt(6)
	v_mfma_f32_16x16x32_bf16 v[92:95], v[44:47], v[158:161], v[92:95]
	v_lshlrev_b32_e32 v208, 16, v43
	v_and_b32_e32 v209, 0xffff0000, v43
	ds_read_b128 v[178:181], v132 offset:256
	ds_read_b128 v[182:185], v132 offset:272
	ds_read_b128 v[146:149], v114 offset:32768
	ds_read_b128 v[150:153], v114 offset:36864
	ds_read_b128 v[154:157], v114 offset:40960
	ds_read_b128 v[158:161], v114 offset:45056
	s_waitcnt lgkmcnt(10)
	v_pk_mul_f32 v[202:203], v[186:187], v[202:203]
	v_pk_mul_f32 v[204:205], v[188:189], v[204:205]
	v_pk_mul_f32 v[206:207], v[190:191], v[206:207]
	v_pk_mul_f32 v[208:209], v[192:193], v[208:209]
	v_cvt_pk_bf16_f32 v40, v202, v203
	v_cvt_pk_bf16_f32 v41, v204, v205
	v_cvt_pk_bf16_f32 v42, v206, v207
	v_cvt_pk_bf16_f32 v43, v208, v209
	s_nop 1
	s_waitcnt lgkmcnt(9)
	v_mfma_f32_16x16x32_bf16 v[80:83], v[40:43], v[162:165], v[80:83]
	v_lshlrev_b32_e32 v194, 16, v36
	v_and_b32_e32 v195, 0xffff0000, v36
	s_waitcnt lgkmcnt(8)
	v_mfma_f32_16x16x32_bf16 v[84:87], v[40:43], v[166:169], v[84:87]
	v_lshlrev_b32_e32 v196, 16, v37
	v_and_b32_e32 v197, 0xffff0000, v37
	s_waitcnt lgkmcnt(7)
	v_mfma_f32_16x16x32_bf16 v[88:91], v[40:43], v[170:173], v[88:91]
	v_lshlrev_b32_e32 v198, 16, v38
	v_and_b32_e32 v199, 0xffff0000, v38
	s_waitcnt lgkmcnt(6)
	v_mfma_f32_16x16x32_bf16 v[92:95], v[40:43], v[174:177], v[92:95]
	v_lshlrev_b32_e32 v200, 16, v39
	v_and_b32_e32 v201, 0xffff0000, v39
	ds_read_b128 v[186:189], v132 offset:384
	ds_read_b128 v[190:193], v132 offset:400
	ds_read_b128 v[162:165], v115 offset:32768
	ds_read_b128 v[166:169], v115 offset:36864
	ds_read_b128 v[170:173], v115 offset:40960
	ds_read_b128 v[174:177], v115 offset:45056
	s_waitcnt lgkmcnt(10)
	v_pk_mul_f32 v[194:195], v[178:179], v[194:195]
	v_pk_mul_f32 v[196:197], v[180:181], v[196:197]
	v_pk_mul_f32 v[198:199], v[182:183], v[198:199]
	v_pk_mul_f32 v[200:201], v[184:185], v[200:201]
	v_cvt_pk_bf16_f32 v36, v194, v195
	v_cvt_pk_bf16_f32 v37, v196, v197
	v_cvt_pk_bf16_f32 v38, v198, v199
	v_cvt_pk_bf16_f32 v39, v200, v201
	s_nop 1
	s_waitcnt lgkmcnt(9)
	v_mfma_f32_16x16x32_bf16 v[80:83], v[36:39], v[146:149], v[80:83]
	v_lshlrev_b32_e32 v202, 16, v32
	v_and_b32_e32 v203, 0xffff0000, v32
	s_waitcnt lgkmcnt(8)
	v_mfma_f32_16x16x32_bf16 v[84:87], v[36:39], v[150:153], v[84:87]
	v_lshlrev_b32_e32 v204, 16, v33
	v_and_b32_e32 v205, 0xffff0000, v33
	s_waitcnt lgkmcnt(7)
	v_mfma_f32_16x16x32_bf16 v[88:91], v[36:39], v[154:157], v[88:91]
	v_lshlrev_b32_e32 v206, 16, v34
	v_and_b32_e32 v207, 0xffff0000, v34
	s_waitcnt lgkmcnt(6)
	v_mfma_f32_16x16x32_bf16 v[92:95], v[36:39], v[158:161], v[92:95]
	v_lshlrev_b32_e32 v208, 16, v35
	v_and_b32_e32 v209, 0xffff0000, v35
	s_waitcnt lgkmcnt(4)
	v_pk_mul_f32 v[202:203], v[186:187], v[202:203]
	v_pk_mul_f32 v[204:205], v[188:189], v[204:205]
	v_pk_mul_f32 v[206:207], v[190:191], v[206:207]
	v_pk_mul_f32 v[208:209], v[192:193], v[208:209]
	v_cvt_pk_bf16_f32 v32, v202, v203
	v_cvt_pk_bf16_f32 v33, v204, v205
	v_cvt_pk_bf16_f32 v34, v206, v207
	v_cvt_pk_bf16_f32 v35, v208, v209
	s_nop 1
	s_waitcnt lgkmcnt(3)
	v_mfma_f32_16x16x32_bf16 v[80:83], v[32:35], v[162:165], v[80:83]
	s_waitcnt lgkmcnt(2)
	v_mfma_f32_16x16x32_bf16 v[84:87], v[32:35], v[166:169], v[84:87]
	s_waitcnt lgkmcnt(1)
	v_mfma_f32_16x16x32_bf16 v[88:91], v[32:35], v[170:173], v[88:91]
	s_waitcnt lgkmcnt(0)
	v_mfma_f32_16x16x32_bf16 v[92:95], v[32:35], v[174:177], v[92:95]
	s_add_i32 s20, s20, s21
	s_barrier
	s_cmp_eq_u32 s19, 12
	s_cbranch_scc1 .Lsc_noiss3
	s_mul_i32 s0, s21, 3
	s_add_i32 s0, s20, s0
	s_lshl_b32 s24, s0, 8
	s_add_i32 s4, s6, 0x8000
	s_mov_b32 m0, s4
	v_lshl_add_u64 v[116:117], v[98:99], 0, s[24:25]
	v_lshl_add_u64 v[118:119], v[100:101], 0, s[24:25]
	global_load_lds_dwordx4 v[116:117], off
	s_add_i32 s4, s4, 0x400
	s_mov_b32 m0, s4
	v_lshl_add_u64 v[120:121], v[96:97], 0, s[24:25]
	global_load_lds_dwordx4 v[118:119], off
	global_load_dwordx4 v[44:47], v[120:121], off
	global_load_dwordx4 v[40:43], v[120:121], off offset:64
	global_load_dwordx4 v[36:39], v[120:121], off offset:128
	global_load_dwordx4 v[32:35], v[120:121], off offset:192
.Lsc_noiss3:
	s_cmp_eq_u32 s19, 12
	s_cbranch_scc1 .Lsc_wl3
	s_waitcnt vmcnt(30)
	s_branch .Lsc_wd3

.Lsc_wd3:
	s_barrier
	s_lshl_b32 s0, s20, 2
	s_add_i32 s0, s0, 0x12010
	v_mov_b32_e32 v116, s0
	v_lshl_add_u32 v132, s20, 9, v103
	ds_read_b32 v218, v116
	ds_read_b128 v[178:181], v132
	ds_read_b128 v[182:185], v132 offset:16
	ds_read_b128 v[146:149], v112 offset:49152
	ds_read_b128 v[150:153], v112 offset:53248
	ds_read_b128 v[154:157], v112 offset:57344
	ds_read_b128 v[158:161], v112 offset:61440
	ds_read_b128 v[186:189], v132 offset:128
	ds_read_b128 v[190:193], v132 offset:144
	ds_read_b128 v[162:165], v113 offset:49152
	ds_read_b128 v[166:169], v113 offset:53248
	ds_read_b128 v[170:173], v113 offset:57344
	ds_read_b128 v[174:177], v113 offset:61440
	s_add_i32 s0, s20, s17
	s_lshl_b32 s0, s0, 5
	s_or_b32 s0, s0, s18
	s_ashr_i32 s1, s0, 31
	s_lshl_b64 s[0:1], s[0:1], 14
	v_lshl_add_u64 v[118:119], v[104:105], 0, s[0:1]
	v_cvt_pk_bf16_f32 v134, v80, v81
	v_cvt_pk_bf16_f32 v135, v82, v83
	v_lshl_add_u64 v[122:123], v[118:119], 0, v[144:145]
	v_cvt_pk_bf16_f32 v136, v84, v85
	v_cvt_pk_bf16_f32 v137, v86, v87
	v_lshl_add_u64 v[124:125], v[118:119], 0, v[106:107]
	v_cvt_pk_bf16_f32 v138, v88, v89
	v_cvt_pk_bf16_f32 v139, v90, v91
	v_lshl_add_u64 v[126:127], v[118:119], 0, v[108:109]
	v_cvt_pk_bf16_f32 v140, v92, v93
	v_cvt_pk_bf16_f32 v141, v94, v95
	v_lshl_add_u64 v[128:129], v[118:119], 0, v[110:111]
	global_store_dwordx2 v[122:123], v[134:135], off
	global_store_dwordx2 v[124:125], v[136:137], off
	global_store_dwordx2 v[126:127], v[138:139], off
	global_store_dwordx2 v[128:129], v[140:141], off
	s_waitcnt lgkmcnt(12)
	v_pk_mul_f32 v[80:81], v[80:81], v[218:219] op_sel_hi:[1,0]
	v_pk_mul_f32 v[82:83], v[82:83], v[218:219] op_sel_hi:[1,0]
	v_pk_mul_f32 v[84:85], v[84:85], v[218:219] op_sel_hi:[1,0]
	v_pk_mul_f32 v[86:87], v[86:87], v[218:219] op_sel_hi:[1,0]
	v_pk_mul_f32 v[88:89], v[88:89], v[218:219] op_sel_hi:[1,0]
	v_pk_mul_f32 v[90:91], v[90:91], v[218:219] op_sel_hi:[1,0]
	v_pk_mul_f32 v[92:93], v[92:93], v[218:219] op_sel_hi:[1,0]
	v_pk_mul_f32 v[94:95], v[94:95], v[218:219] op_sel_hi:[1,0]
	v_lshlrev_b32_e32 v194, 16, v60
	v_and_b32_e32 v195, 0xffff0000, v60
	v_lshlrev_b32_e32 v196, 16, v61
	v_and_b32_e32 v197, 0xffff0000, v61
	v_lshlrev_b32_e32 v198, 16, v62
	v_and_b32_e32 v199, 0xffff0000, v62
	v_lshlrev_b32_e32 v200, 16, v63
	v_and_b32_e32 v201, 0xffff0000, v63
	s_waitcnt lgkmcnt(10)
	v_pk_mul_f32 v[194:195], v[178:179], v[194:195]
	v_pk_mul_f32 v[196:197], v[180:181], v[196:197]
	v_pk_mul_f32 v[198:199], v[182:183], v[198:199]
	v_pk_mul_f32 v[200:201], v[184:185], v[200:201]
	v_cvt_pk_bf16_f32 v60, v194, v195
	v_cvt_pk_bf16_f32 v61, v196, v197
	v_cvt_pk_bf16_f32 v62, v198, v199
	v_cvt_pk_bf16_f32 v63, v200, v201
	s_nop 1
	s_waitcnt lgkmcnt(9)
	v_mfma_f32_16x16x32_bf16 v[80:83], v[60:63], v[146:149], v[80:83]
	v_lshlrev_b32_e32 v202, 16, v56
	v_and_b32_e32 v203, 0xffff0000, v56
	s_waitcnt lgkmcnt(8)
	v_mfma_f32_16x16x32_bf16 v[84:87], v[60:63], v[150:153], v[84:87]
	v_lshlrev_b32_e32 v204, 16, v57
	v_and_b32_e32 v205, 0xffff0000, v57
	s_waitcnt lgkmcnt(7)
	v_mfma_f32_16x16x32_bf16 v[88:91], v[60:63], v[154:157], v[88:91]
	v_lshlrev_b32_e32 v206, 16, v58
	v_and_b32_e32 v207, 0xffff0000, v58
	s_waitcnt lgkmcnt(6)
	v_mfma_f32_16x16x32_bf16 v[92:95], v[60:63], v[158:161], v[92:95]
	v_lshlrev_b32_e32 v208, 16, v59
	v_and_b32_e32 v209, 0xffff0000, v59
	ds_read_b128 v[178:181], v132 offset:256
	ds_read_b128 v[182:185], v132 offset:272
	ds_read_b128 v[146:149], v114 offset:49152
	ds_read_b128 v[150:153], v114 offset:53248
	ds_read_b128 v[154:157], v114 offset:57344
	ds_read_b128 v[158:161], v114 offset:61440
	s_waitcnt lgkmcnt(10)
	v_pk_mul_f32 v[202:203], v[186:187], v[202:203]
	v_pk_mul_f32 v[204:205], v[188:189], v[204:205]
	v_pk_mul_f32 v[206:207], v[190:191], v[206:207]
	v_pk_mul_f32 v[208:209], v[192:193], v[208:209]
	v_cvt_pk_bf16_f32 v56, v202, v203
	v_cvt_pk_bf16_f32 v57, v204, v205
	v_cvt_pk_bf16_f32 v58, v206, v207
	v_cvt_pk_bf16_f32 v59, v208, v209
	s_nop 1
	s_waitcnt lgkmcnt(9)
	v_mfma_f32_16x16x32_bf16 v[80:83], v[56:59], v[162:165], v[80:83]
	v_lshlrev_b32_e32 v194, 16, v52
	v_and_b32_e32 v195, 0xffff0000, v52
	s_waitcnt lgkmcnt(8)
	v_mfma_f32_16x16x32_bf16 v[84:87], v[56:59], v[166:169], v[84:87]
	v_lshlrev_b32_e32 v196, 16, v53
	v_and_b32_e32 v197, 0xffff0000, v53
	s_waitcnt lgkmcnt(7)
	v_mfma_f32_16x16x32_bf16 v[88:91], v[56:59], v[170:173], v[88:91]
	v_lshlrev_b32_e32 v198, 16, v54
	v_and_b32_e32 v199, 0xffff0000, v54
	s_waitcnt lgkmcnt(6)
	v_mfma_f32_16x16x32_bf16 v[92:95], v[56:59], v[174:177], v[92:95]
	v_lshlrev_b32_e32 v200, 16, v55
	v_and_b32_e32 v201, 0xffff0000, v55
	ds_read_b128 v[186:189], v132 offset:384
	ds_read_b128 v[190:193], v132 offset:400
	ds_read_b128 v[162:165], v115 offset:49152
	ds_read_b128 v[166:169], v115 offset:53248
	ds_read_b128 v[170:173], v115 offset:57344
	ds_read_b128 v[174:177], v115 offset:61440
	s_waitcnt lgkmcnt(10)
	v_pk_mul_f32 v[194:195], v[178:179], v[194:195]
	v_pk_mul_f32 v[196:197], v[180:181], v[196:197]
	v_pk_mul_f32 v[198:199], v[182:183], v[198:199]
	v_pk_mul_f32 v[200:201], v[184:185], v[200:201]
	v_cvt_pk_bf16_f32 v52, v194, v195
	v_cvt_pk_bf16_f32 v53, v196, v197
	v_cvt_pk_bf16_f32 v54, v198, v199
	v_cvt_pk_bf16_f32 v55, v200, v201
	s_nop 1
	s_waitcnt lgkmcnt(9)
	v_mfma_f32_16x16x32_bf16 v[80:83], v[52:55], v[146:149], v[80:83]
	v_lshlrev_b32_e32 v202, 16, v48
	v_and_b32_e32 v203, 0xffff0000, v48
	s_waitcnt lgkmcnt(8)
	v_mfma_f32_16x16x32_bf16 v[84:87], v[52:55], v[150:153], v[84:87]
	v_lshlrev_b32_e32 v204, 16, v49
	v_and_b32_e32 v205, 0xffff0000, v49
	s_waitcnt lgkmcnt(7)
	v_mfma_f32_16x16x32_bf16 v[88:91], v[52:55], v[154:157], v[88:91]
	v_lshlrev_b32_e32 v206, 16, v50
	v_and_b32_e32 v207, 0xffff0000, v50
	s_waitcnt lgkmcnt(6)
	v_mfma_f32_16x16x32_bf16 v[92:95], v[52:55], v[158:161], v[92:95]
	v_lshlrev_b32_e32 v208, 16, v51
	v_and_b32_e32 v209, 0xffff0000, v51
	s_waitcnt lgkmcnt(4)
	v_pk_mul_f32 v[202:203], v[186:187], v[202:203]
	v_pk_mul_f32 v[204:205], v[188:189], v[204:205]
	v_pk_mul_f32 v[206:207], v[190:191], v[206:207]
	v_pk_mul_f32 v[208:209], v[192:193], v[208:209]
	v_cvt_pk_bf16_f32 v48, v202, v203
	v_cvt_pk_bf16_f32 v49, v204, v205
	v_cvt_pk_bf16_f32 v50, v206, v207
	v_cvt_pk_bf16_f32 v51, v208, v209
	s_nop 1
	s_waitcnt lgkmcnt(3)
	v_mfma_f32_16x16x32_bf16 v[80:83], v[48:51], v[162:165], v[80:83]
	s_waitcnt lgkmcnt(2)
	v_mfma_f32_16x16x32_bf16 v[84:87], v[48:51], v[166:169], v[84:87]
	s_waitcnt lgkmcnt(1)
	v_mfma_f32_16x16x32_bf16 v[88:91], v[48:51], v[170:173], v[88:91]
	s_waitcnt lgkmcnt(0)
	v_mfma_f32_16x16x32_bf16 v[92:95], v[48:51], v[174:177], v[92:95]
	s_add_i32 s20, s20, s21
	s_barrier
	s_add_i32 s19, s19, 4
	s_cmp_lt_u32 s19, 16
	s_cbranch_scc1 .Lsc_loop
	s_branch .LBB0_865
